# stack on v054: counted unit-boundary waits (8 phases) + trailing-half offset barrier at the K-loop entry + pipelined LDS reads in the mixer's kk=2/3 MFMA blocks
# baseline (speedup 1.0000x reference)
.Lrb_skip0:
.LBB0_323:
	s_add_u32 s26, s24, 0xfffc0080
	s_addc_u32 s27, s25, -1
	s_add_i32 s36, 0, 0x10000
	s_cmp_eq_u32 s21, 12
	s_cselect_b32 s57, s17, s27
	s_cselect_b32 s56, s16, s26
	v_add_u32_e32 v142, s36, v161
	s_cselect_b32 s27, s19, s15
	s_cselect_b32 s26, s18, s13
	s_add_i32 s38, 0, 0x14000
	ds_read_b128 v[144:147], v142
	ds_read_b128 v[148:151], v142 offset:1024
	ds_read_b128 v[152:155], v142 offset:2048
	ds_read_b128 v[178:181], v142 offset:3072
	v_add_u32_e32 v142, s38, v161
	ds_read_b128 v[182:185], v142
	ds_read_b128 v[186:189], v142 offset:1024
	ds_read_b128 v[190:193], v142 offset:2048
	ds_read_b128 v[194:197], v142 offset:3072
	v_lshl_add_u64 v[156:157], s[24:25], 0, v[140:141]
	s_add_i32 m0, s68, 0xc000
	ds_read_b128 v[198:201], v177
	ds_read_b128 v[202:205], v177 offset:1024
	ds_read_b128 v[206:209], v177 offset:2048
	ds_read_b128 v[210:213], v177 offset:3072
	ds_read_b128 v[214:217], v177 offset:4096
	ds_read_b128 v[222:225], v177 offset:5120
	ds_read_b128 v[226:229], v177 offset:6144
	ds_read_b128 v[230:233], v177 offset:7168
	global_load_lds_dwordx4 v[156:157], off
	v_lshl_add_u64 v[156:157], s[24:25], 0, v[138:139]
	s_add_i32 m0, s68, 0xe000
	s_nop 0
	global_load_lds_dwordx4 v[156:157], off
	s_waitcnt vmcnt(18)
	s_cmp_eq_i32 s21, -2
	s_cselect_b32 s100, s101, 0
	s_cmp_lg_u32 s100, 0
	s_cbranch_scc1 .Lrw_skip323_0
	s_waitcnt vmcnt(8)

.LBB0_329:
	s_mov_b32 s101, 1
	s_andn2_b64 vcc, exec, s[8:9]
	s_cbranch_vccnz .LBB0_312
	s_branch .LBB0_312

.Lrb_skip1:
.LBB0_437:
	s_add_u32 s26, s24, 0x4000
	s_addc_u32 s27, s25, 0
	s_cmpk_eq_i32 s82, 0x54
	s_cselect_b32 s58, s20, s26
	s_cselect_b32 s59, s21, s27
	s_cselect_b32 s56, s22, s80
	s_cselect_b32 s57, s23, s81
	s_add_u32 s26, s58, 0x8000
	s_addc_u32 s27, s59, 0
	s_add_i32 s36, 0, 0x10000
	s_add_i32 s38, 0, 0x14000
	v_add_u32_e32 v126, s36, v197
	v_add_u32_e32 v168, s38, v197
	ds_read_b128 v[114:117], v126
	ds_read_b128 v[118:121], v126 offset:1024
	ds_read_b128 v[122:125], v126 offset:2048
	ds_read_b128 v[126:129], v126 offset:3072
	ds_read_b128 v[138:141], v168
	ds_read_b128 v[142:145], v168 offset:1024
	ds_read_b128 v[154:157], v168 offset:2048
	ds_read_b128 v[178:181], v168 offset:3072
	v_lshl_add_u64 v[194:195], s[24:25], 0, v[176:177]
	s_add_i32 m0, s63, 0xc000
	ds_read_b128 v[182:185], v199
	ds_read_b128 v[186:189], v199 offset:1024
	ds_read_b128 v[190:193], v199 offset:2048
	ds_read_b128 v[200:203], v199 offset:3072
	ds_read_b128 v[204:207], v199 offset:4096
	ds_read_b128 v[208:211], v199 offset:5120
	ds_read_b128 v[212:215], v199 offset:6144
	ds_read_b128 v[222:225], v199 offset:7168
	global_load_lds_dwordx4 v[194:195], off
	v_lshl_add_u64 v[194:195], s[24:25], 0, v[174:175]
	s_add_i32 m0, s63, 0xe000
	s_nop 0
	global_load_lds_dwordx4 v[194:195], off
	s_waitcnt vmcnt(56)
	s_cmp_eq_i32 s82, -2
	s_cselect_b32 s100, s101, 0
	s_cmp_lg_u32 s100, 0
	s_cbranch_scc1 .Lrw_skip437_0
	s_waitcnt vmcnt(8)

.LBB0_456:
	s_or_b64 exec, exec, s[24:25]
	s_and_b64 vcc, exec, s[6:7]
	s_mov_b64 s[6:7], -1
	s_cbranch_vccnz .LBB0_423
	s_mov_b32 s101, 1
	s_andn2_b64 vcc, exec, s[8:9]
	s_cbranch_vccnz .LBB0_422
	s_branch .LBB0_422

.Lrb_skip2:
.LBB0_643:
	s_add_u32 s36, s58, 0xfff80080
	s_addc_u32 s37, s59, -1
	s_add_i32 s38, 0, 0x10000
	s_cmp_eq_u32 s64, 28
	s_cselect_b32 s63, s23, s37
	s_cselect_b32 s62, s22, s36
	s_cselect_b32 s61, s25, s57
	s_cselect_b32 s60, s24, s21
	s_add_i32 s39, 0, 0x14000
	v_add_u32_e32 v152, s38, v161
	v_add_u32_e32 v156, s39, v161
	ds_read_b128 v[140:143], v152
	ds_read_b128 v[144:147], v152 offset:1024
	ds_read_b128 v[148:151], v152 offset:2048
	ds_read_b128 v[152:155], v152 offset:3072
	ds_read_b128 v[180:183], v156
	ds_read_b128 v[184:187], v156 offset:1024
	ds_read_b128 v[188:191], v156 offset:2048
	ds_read_b128 v[192:195], v156 offset:3072
	v_lshl_add_u64 v[172:173], s[58:59], 0, v[138:139]
	s_add_i32 m0, s41, 0xc000
	ds_read_b128 v[196:199], v179
	ds_read_b128 v[200:203], v179 offset:1024
	ds_read_b128 v[204:207], v179 offset:2048
	ds_read_b128 v[208:211], v179 offset:3072
	ds_read_b128 v[212:215], v179 offset:4096
	ds_read_b128 v[222:225], v179 offset:5120
	ds_read_b128 v[226:229], v179 offset:6144
	ds_read_b128 v[230:233], v179 offset:7168
	global_load_lds_dwordx4 v[172:173], off
	v_lshl_add_u64 v[172:173], s[58:59], 0, v[136:137]
	s_add_i32 m0, s41, 0xe000
	s_nop 0
	global_load_lds_dwordx4 v[172:173], off
	s_waitcnt vmcnt(24)
	s_cmp_eq_i32 s64, -2
	s_cselect_b32 s100, s101, 0
	s_cmp_lg_u32 s100, 0
	s_cbranch_scc1 .Lrw_skip643_0
	s_waitcnt vmcnt(8)

.LBB0_667:
	s_and_b64 vcc, exec, s[6:7]
	s_mov_b64 s[6:7], -1
	s_cbranch_vccnz .LBB0_628
	s_ashr_i32 s21, s20, 31
	s_and_b32 s27, s82, 1
	s_lshl_b64 s[6:7], s[20:21], 11
	v_mov_b32_e32 v2, v157
	s_add_u32 s6, s29, s6
	s_addc_u32 s7, s71, s7
	s_waitcnt lgkmcnt(0)
	v_ashrrev_i32_e32 v3, 31, v2
	v_lshl_add_u64 v[2:3], v[2:3], 2, s[6:7]
	s_mul_i32 s6, s27, 0x1400
	s_add_i32 m0, s73, s6
	s_mov_b32 s101, 1
	s_andn2_b64 vcc, exec, s[10:11]
	global_load_lds_dword v[2:3], off
	s_cbranch_vccnz .LBB0_627
	s_branch .LBB0_627

.Lrb_skip3:
.LBB0_696:
	s_add_u32 s36, s26, 0xfffc0080
	s_addc_u32 s37, s27, -1
	s_add_i32 s38, 0, 0x10000
	s_cmp_eq_u32 s60, 12
	s_cselect_b32 s59, s19, s37
	s_cselect_b32 s58, s18, s36
	v_add_u32_e32 v140, s38, v149
	s_cselect_b32 s57, s21, s17
	s_cselect_b32 s56, s20, s15
	s_add_i32 s39, 0, 0x14000
	ds_read_b128 v[156:159], v140
	ds_read_b128 v[172:175], v140 offset:1024
	ds_read_b128 v[190:193], v140 offset:2048
	ds_read_b128 v[194:197], v140 offset:3072
	v_add_u32_e32 v140, s39, v149
	ds_read_b128 v[198:201], v140
	ds_read_b128 v[202:205], v140 offset:1024
	ds_read_b128 v[206:209], v140 offset:2048
	ds_read_b128 v[210:213], v140 offset:3072
	v_lshl_add_u64 v[160:161], s[26:27], 0, v[138:139]
	s_add_i32 m0, s25, 0xc000
	ds_read_b128 v[214:217], v189
	ds_read_b128 v[222:225], v189 offset:1024
	ds_read_b128 v[226:229], v189 offset:2048
	ds_read_b128 v[230:233], v189 offset:3072
	ds_read_b128 v[234:237], v189 offset:4096
	ds_read_b128 v[238:241], v189 offset:5120
	ds_read_b128 v[242:245], v189 offset:6144
	ds_read_b128 v[246:249], v189 offset:7168
	global_load_lds_dwordx4 v[160:161], off
	v_lshl_add_u64 v[160:161], s[26:27], 0, v[136:137]
	s_add_i32 m0, s25, 0xe000
	s_nop 0
	global_load_lds_dwordx4 v[160:161], off
	s_waitcnt vmcnt(25)
	s_cmp_eq_i32 s60, -2
	s_cselect_b32 s100, s101, 0
	s_cmp_lg_u32 s100, 0
	s_cbranch_scc1 .Lrw_skip696_0
	s_waitcnt vmcnt(8)

.LBB0_702:
	s_mov_b32 s101, 1
	s_andn2_b64 vcc, exec, s[10:11]
	s_cbranch_vccnz .LBB0_684
	s_branch .LBB0_684

.Lrb_skip5:
.LBB0_1211:
	s_add_u32 s36, s56, 0xfff80080
	s_addc_u32 s37, s57, -1
	s_add_i32 s38, 0, 0x10000
	s_cmp_eq_u32 s78, 28
	s_cselect_b32 s61, s21, s37
	s_cselect_b32 s60, s20, s36
	s_cselect_b32 s59, s23, s62
	s_cselect_b32 s58, s22, s25
	s_add_i32 s39, 0, 0x14000
	v_add_u32_e32 v142, s38, v201
	v_add_u32_e32 v168, s39, v201
	ds_read_b128 v[110:113], v142
	ds_read_b128 v[118:121], v142 offset:1024
	ds_read_b128 v[138:141], v142 offset:2048
	ds_read_b128 v[142:145], v142 offset:3072
	ds_read_b128 v[146:149], v168
	ds_read_b128 v[150:153], v168 offset:1024
	ds_read_b128 v[174:177], v168 offset:2048
	ds_read_b128 v[178:181], v168 offset:3072
	v_lshl_add_u64 v[168:169], s[56:57], 0, v[172:173]
	s_add_i32 m0, s66, 0xc000
	ds_read_b128 v[182:185], v203
	ds_read_b128 v[186:189], v203 offset:1024
	ds_read_b128 v[190:193], v203 offset:2048
	ds_read_b128 v[194:197], v203 offset:3072
	ds_read_b128 v[204:207], v203 offset:4096
	ds_read_b128 v[208:211], v203 offset:5120
	ds_read_b128 v[212:215], v203 offset:6144
	ds_read_b128 v[222:225], v203 offset:7168
	global_load_lds_dwordx4 v[168:169], off
	v_lshl_add_u64 v[168:169], s[56:57], 0, v[160:161]
	s_add_i32 m0, s66, 0xe000
	s_nop 0
	global_load_lds_dwordx4 v[168:169], off
	s_waitcnt vmcnt(63)
	s_cmp_eq_i32 s78, -2
	s_cselect_b32 s100, s101, 0
	s_cmp_lg_u32 s100, 0
	s_cbranch_scc1 .Lrw_skip1211_0
	s_waitcnt vmcnt(8)

.Lrb_skip6:
.LBB0_1332:
	s_add_u32 s26, s24, 0xfffc0080
	s_addc_u32 s27, s25, -1
	s_add_i32 s36, 0, 0x10000
	s_cmp_eq_u32 s21, 12
	s_cselect_b32 s57, s17, s27
	s_cselect_b32 s56, s16, s26
	v_add_u32_e32 v142, s36, v161
	s_cselect_b32 s27, s19, s15
	s_cselect_b32 s26, s18, s13
	s_add_i32 s38, 0, 0x14000
	ds_read_b128 v[144:147], v142
	ds_read_b128 v[148:151], v142 offset:1024
	ds_read_b128 v[152:155], v142 offset:2048
	ds_read_b128 v[178:181], v142 offset:3072
	v_add_u32_e32 v142, s38, v161
	ds_read_b128 v[182:185], v142
	ds_read_b128 v[186:189], v142 offset:1024
	ds_read_b128 v[190:193], v142 offset:2048
	ds_read_b128 v[194:197], v142 offset:3072
	v_lshl_add_u64 v[156:157], s[24:25], 0, v[140:141]
	s_add_i32 m0, s69, 0xc000
	ds_read_b128 v[198:201], v177
	ds_read_b128 v[202:205], v177 offset:1024
	ds_read_b128 v[206:209], v177 offset:2048
	ds_read_b128 v[210:213], v177 offset:3072
	ds_read_b128 v[214:217], v177 offset:4096
	ds_read_b128 v[222:225], v177 offset:5120
	ds_read_b128 v[226:229], v177 offset:6144
	ds_read_b128 v[230:233], v177 offset:7168
	global_load_lds_dwordx4 v[156:157], off
	v_lshl_add_u64 v[156:157], s[24:25], 0, v[138:139]
	s_add_i32 m0, s69, 0xe000
	s_nop 0
	global_load_lds_dwordx4 v[156:157], off
	s_waitcnt vmcnt(18)
	s_cmp_eq_i32 s21, -2
	s_cselect_b32 s100, s101, 0
	s_cmp_lg_u32 s100, 0
	s_cbranch_scc1 .Lrw_skip1332_0
	s_waitcnt vmcnt(8)

.Lrb_skip7:
.LBB0_1446:
	s_add_u32 s8, s26, 0x4000
	s_addc_u32 s9, s27, 0
	s_cmpk_eq_i32 s84, 0x54
	s_cselect_b32 s60, s22, s8
	s_cselect_b32 s61, s23, s9
	s_cselect_b32 s58, s24, s82
	s_cselect_b32 s59, s25, s83
	s_add_u32 s56, s60, 0x8000
	s_addc_u32 s57, s61, 0
	s_add_i32 s8, 0, 0x10000
	s_add_i32 s36, 0, 0x14000
	v_add_u32_e32 v142, s8, v201
	v_add_u32_e32 v168, s36, v201
	ds_read_b128 v[110:113], v142
	ds_read_b128 v[118:121], v142 offset:1024
	ds_read_b128 v[138:141], v142 offset:2048
	ds_read_b128 v[142:145], v142 offset:3072
	ds_read_b128 v[146:149], v168
	ds_read_b128 v[150:153], v168 offset:1024
	ds_read_b128 v[174:177], v168 offset:2048
	ds_read_b128 v[178:181], v168 offset:3072
	v_lshl_add_u64 v[168:169], s[26:27], 0, v[172:173]
	s_add_i32 m0, s65, 0xc000
	ds_read_b128 v[182:185], v203
	ds_read_b128 v[186:189], v203 offset:1024
	ds_read_b128 v[190:193], v203 offset:2048
	ds_read_b128 v[194:197], v203 offset:3072
	ds_read_b128 v[204:207], v203 offset:4096
	ds_read_b128 v[208:211], v203 offset:5120
	ds_read_b128 v[212:215], v203 offset:6144
	ds_read_b128 v[222:225], v203 offset:7168
	global_load_lds_dwordx4 v[168:169], off
	v_lshl_add_u64 v[168:169], s[26:27], 0, v[160:161]
	s_add_i32 m0, s65, 0xe000
	s_nop 0
	global_load_lds_dwordx4 v[168:169], off
	s_waitcnt vmcnt(63)
	s_cmp_eq_i32 s84, -2
	s_cselect_b32 s100, s101, 0
	s_cmp_lg_u32 s100, 0
	s_cbranch_scc1 .Lrw_skip1446_0
	s_waitcnt vmcnt(8)

.LBB0_1465:
	s_or_b64 exec, exec, s[26:27]
	s_and_b64 vcc, exec, s[6:7]
	s_mov_b64 s[6:7], -1
	s_cbranch_vccnz .LBB0_1432
	s_mov_b32 s101, 1
	s_andn2_b64 vcc, exec, s[10:11]
	s_cbranch_vccnz .LBB0_1431
	s_branch .LBB0_1431

.Lrb_skip9:
.LBB0_1615:
	s_add_u32 s31, s64, 0xfffc0080
	s_addc_u32 s36, s65, -1
	s_add_i32 s37, 0, 0x10000
	s_cmp_eq_u32 s27, 12
	s_cselect_b32 vcc_hi, s57, s36
	s_cselect_b32 vcc_lo, s56, s31
	s_cselect_b32 s67, s59, s26
	s_cselect_b32 s66, s58, s25
	s_add_i32 s31, 0, 0x14000
	v_add_u32_e32 v142, s37, v201
	v_add_u32_e32 v158, s31, v201
	ds_read_b128 v[66:69], v142
	ds_read_b128 v[70:73], v142 offset:1024
	ds_read_b128 v[138:141], v142 offset:2048
	ds_read_b128 v[142:145], v142 offset:3072
	ds_read_b128 v[146:149], v158
	ds_read_b128 v[150:153], v158 offset:1024
	ds_read_b128 v[154:157], v158 offset:2048
	ds_read_b128 v[158:161], v158 offset:3072
	v_lshl_add_u64 v[168:169], s[64:65], 0, v[180:181]
	s_add_i32 m0, s63, 0xc000
	ds_read_b128 v[182:185], v222
	ds_read_b128 v[186:189], v222 offset:1024
	ds_read_b128 v[190:193], v222 offset:2048
	ds_read_b128 v[202:205], v222 offset:3072
	ds_read_b128 v[206:209], v222 offset:4096
	ds_read_b128 v[210:213], v222 offset:5120
	ds_read_b128 v[224:227], v222 offset:6144
	ds_read_b128 v[228:231], v222 offset:7168
	global_load_lds_dwordx4 v[168:169], off
	v_lshl_add_u64 v[168:169], s[64:65], 0, v[178:179]
	s_add_i32 m0, s63, 0xe000
	s_nop 0
	global_load_lds_dwordx4 v[168:169], off
	s_waitcnt vmcnt(63)
	s_cmp_eq_i32 s27, -2
	s_cselect_b32 s100, s101, 0
	s_cmp_lg_u32 s100, 0
	s_cbranch_scc1 .Lrw_skip1615_0
	s_waitcnt vmcnt(8)

.LBB0_1637:
	s_mov_b32 s101, 1
	s_andn2_b64 vcc, exec, s[12:13]
	s_cbranch_vccnz .LBB0_1599
	s_branch .LBB0_1599
